# MLA attention loop: one lgkmcnt wait per group of four MFMAs, Q-fragment vmcnt ladder replaced by a single wait before the loop
# baseline (speedup 1.0000x reference)
; template <int DQK, bool SWA>
; DI void attn_item(const P& p, char* shm, int b, int head, int qtile) {
;     ...
;     for (int v = 0; v < 4; ++v)
; #pragma unroll
;         for (int r = 0; r < 16; ++r) oT[v][r] = 0.f;
;     constexpr int NKL = (64 * NKC) / NTHR;
;     bf16x8 kreg[NKL], vreg[2];
;     auto kp_of = [&](int t) { return t < 4 ? 64 * t : CTXL + 64 * (lo + t - 4); };
;     const int kc0 = tid, kc1 = tid + NTHR;
;     const int kld = SWA ? 256 : 1024;
;     const int koff0 = (kc0 >> 4) * kld + (kc0 & 15) * 8, koff1 = (kc1 >> 4) * kld + (kc1 & 15) * 8, koff2 = tid * 8;
;     const int klds0 = (kc0 >> 4) * KST + (kc0 & 15) * 16, klds1 = (kc1 >> 4) * KST + (kc1 & 15) * 16, klds2 = (tid >> 3) * KST + (16 + (tid & 7)) * 16;
;     const int vlds0 = (kc0 >> 3) * VST + (kc0 & 7) * 16, vlds1 = (kc1 >> 3) * VST + (kc1 & 7) * 16;
;     auto load_tile = [&](int t) {
;         const int kp0 = kp_of(t);
;         const size_t ur0 = (size_t)b * PB + kp0;
;         if (SWA) {
;             const bf16_t* kb = KA + ur0 * 256 + kvh * 128;
;             kreg[0] = *(const bf16x8*)(kb + koff0);
;             kreg[1] = *(const bf16x8*)(kb + koff1);
;         } else {
;             const bf16_t* kb = KN + ur0 * 1024 + head * 128;
;             kreg[0] = *(const bf16x8*)(kb + koff0);
;             kreg[1] = *(const bf16x8*)(kb + koff1);
;             kreg[NKL - 1] = *(const bf16x8*)(KR + ur0 * 64 + koff2);
;         }
;         const bf16_t* vb_ = VT + (((size_t)b * (PB / 64) + (kp0 >> 6)) * (nhv * 128) + kvh * 128) * 64;
;         vreg[0] = *(const bf16x8*)(vb_ + kc0 * 8);
;         vreg[1] = *(const bf16x8*)(vb_ + kc1 * 8);
;     };
;     auto store_tile = [&](int t) {
;         const int bo = (t & 1) * (64 * KST + 128 * VST);
;         *(bf16x8*)(Ks + bo + klds0) = kreg[0];
;         *(bf16x8*)(Ks + bo + klds1) = kreg[1];
;         if (!SWA) *(bf16x8*)(Ks + bo + klds2) = kreg[NKL - 1];
; #pragma unroll
;         for (int i = 0; i < 2; ++i) {
;             const s16x4 w0 = __builtin_shufflevector(vreg[i], vreg[i], 0, 1, 2, 3), w1 = __builtin_shufflevector(vreg[i], vreg[i], 4, 5, 6, 7);
;             char* dstv = Vs + bo + (i ? vlds1 : vlds0);
;             *(s16x4*)dstv = w0;
;             *(s16x4*)(dstv + 8) = w1;
;         }
;     };
;     constexpr int TB = 64 * KST + 128 * VST;
;     load_tile(0);
;     store_tile(0);
;     load_tile(1);
;     __syncthreads();
.LBB0_1166:
	v_mov_b32_e32 v36, v206
	s_lshl_b32 s0, s23, 8
	s_addk_i32 s0, 0x100
	v_and_b32_e32 v37, 31, v36
	v_ashrrev_i32_e32 v2, 1, v36
	s_lshr_b32 s12, s97, 3
	v_and_b32_e32 v2, 0xffffffe0, v2
	v_or_b32_e32 v3, s0, v37
	v_add_u32_e32 v38, 0x200, v36
	v_lshlrev_b32_e32 v10, 3, v36
	s_and_b32 s16, s97, 7
	v_add_u32_e32 v22, v3, v2
	v_lshlrev_b32_e32 v2, 6, v36
	v_and_b32_e32 v3, 0x78, v10
	v_lshlrev_b32_e32 v18, 3, v38
	s_mul_i32 s23, s12, 0x880000
	v_and_or_b32 v2, v2, s74, v3
	v_lshlrev_b32_e32 v3, 6, v38
	v_and_b32_e32 v4, 0x78, v18
	s_mul_hi_u32 s19, s12, 0x880000
	s_add_u32 s0, s39, s23
	v_and_or_b32 v4, v3, s74, v4
	s_addc_u32 s1, s40, s19
	s_lshl_b32 s18, s16, 7
	s_lshl_b32 s28, s16, 8
	s_add_u32 s0, s0, s28
	v_ashrrev_i32_e32 v3, 31, v2
	v_ashrrev_i32_e32 v5, 31, v4
	s_addc_u32 s1, s1, 0
	v_lshlrev_b64 v[24:25], 1, v[2:3]
	v_lshlrev_b64 v[26:27], 1, v[4:5]
	s_mul_i32 s55, s12, 0x88000
	v_lshl_add_u64 v[2:3], s[0:1], 0, v[24:25]
	v_lshl_add_u64 v[6:7], s[0:1], 0, v[26:27]
	s_mul_hi_u32 s29, s12, 0x88000
	s_add_u32 s0, s10, s55
	v_ashrrev_i32_e32 v11, 31, v10
	s_addc_u32 s1, s11, s29
	v_lshlrev_b64 v[28:29], 1, v[10:11]
	v_ashrrev_i32_e32 v23, 31, v22
	v_lshl_add_u64 v[10:11], s[0:1], 0, v[28:29]
	s_add_u32 s0, s41, s23
	v_mad_u64_u32 v[182:183], s[20:21], s12, v204, v[22:23]
	v_mov_b64_e32 v[22:23], s[8:9]
	s_addc_u32 s1, s54, s19
	s_lshl_b32 s77, s16, 14
	v_mad_u64_u32 v[22:23], s[20:21], v182, s75, v[22:23]
	v_bfe_u32 v0, v36, 5, 1
	s_add_u32 s0, s0, s77
	v_ashrrev_i32_e32 v19, 31, v18
	s_mul_hi_u32 s17, s12, 0x1100
	s_mul_i32 s82, s12, 0x1100
	v_mad_i32_i24 v23, v183, s75, v23
	s_mul_i32 s12, s16, 0x180
	s_addc_u32 s1, s1, 0
	v_lshlrev_b64 v[30:31], 1, v[18:19]
	v_lshl_add_u64 v[22:23], v[22:23], 0, s[12:13]
	v_lshlrev_b32_e32 v32, 4, v0
	v_mov_b32_e32 v33, v1
	v_lshl_add_u64 v[14:15], s[0:1], 0, v[28:29]
	v_lshl_add_u64 v[18:19], s[0:1], 0, v[30:31]
	v_lshl_add_u64 v[22:23], v[22:23], 0, v[32:33]
	s_or_b32 s16, s82, 64
	global_load_dwordx4 v[2:5], v[2:3], off
	s_nop 0
	global_load_dwordx4 v[6:9], v[6:7], off
	s_lshl_b64 s[20:21], s[16:17], 11
	global_load_dwordx4 v[10:13], v[10:11], off
	s_add_u32 s12, s39, s20
	global_load_dwordx4 v[14:17], v[14:15], off
	s_addc_u32 s21, s40, s21
	global_load_dwordx4 v[18:21], v[18:19], off
	s_nop 0
	global_load_dwordx4 v[142:145], v[22:23], off
	global_load_dwordx4 v[138:141], v[22:23], off offset:32
	global_load_dwordx4 v[134:137], v[22:23], off offset:64
	global_load_dwordx4 v[130:133], v[22:23], off offset:96
	global_load_dwordx4 v[126:129], v[22:23], off offset:128
	global_load_dwordx4 v[122:125], v[22:23], off offset:160
	global_load_dwordx4 v[118:121], v[22:23], off offset:192
	global_load_dwordx4 v[114:117], v[22:23], off offset:224
	global_load_dwordx4 v[110:113], v[22:23], off offset:256
	global_load_dwordx4 v[106:109], v[22:23], off offset:288
	global_load_dwordx4 v[102:105], v[22:23], off offset:320
	global_load_dwordx4 v[98:101], v[22:23], off offset:352
	s_add_u32 s20, s12, s28
	s_addc_u32 s21, s21, 0
	s_lshl_b64 s[16:17], s[16:17], 7
	s_add_u32 s16, s10, s16
	s_addc_u32 s17, s11, s17
	v_lshl_add_u64 v[22:23], s[20:21], 0, v[24:25]
	s_add_u32 s0, s0, 0x20000
	global_load_dwordx4 v[146:149], v[22:23], off
	v_lshl_add_u64 v[22:23], s[20:21], 0, v[26:27]
	s_addc_u32 s1, s1, 0
	v_lshl_add_u64 v[34:35], s[16:17], 0, v[28:29]
	global_load_dwordx4 v[150:153], v[22:23], off
	global_load_dwordx4 v[154:157], v[34:35], off
	v_lshl_add_u64 v[22:23], s[0:1], 0, v[28:29]
	v_lshl_add_u64 v[34:35], s[0:1], 0, v[30:31]
	global_load_dwordx4 v[162:165], v[22:23], off
	global_load_dwordx4 v[158:161], v[34:35], off
	v_lshlrev_b32_e32 v33, 4, v36
	v_lshrrev_b32_e32 v23, 4, v36
	v_and_b32_e32 v22, 0xf0, v33
	v_lshlrev_b32_e32 v34, 4, v38
	v_mad_u64_u32 v[190:191], s[0:1], v23, s76, v[22:23]
	v_lshrrev_b32_e32 v23, 4, v38
	v_and_b32_e32 v22, 0xf0, v34
	v_mad_u64_u32 v[192:193], s[0:1], v23, s76, v[22:23]
	v_ashrrev_i32_e32 v23, 3, v36
	v_and_b32_e32 v22, 0x70, v33
	v_lshrrev_b32_e32 v33, 3, v38
	v_and_b32_e32 v34, 0x70, v34
	v_mad_u64_u32 v[184:185], s[0:1], v23, s60, v[22:23]
	v_mad_u64_u32 v[186:187], s[0:1], v33, s60, v[34:35]
	v_add_u32_e32 v191, 16, v190
	v_mad_u64_u32 v[188:189], s[0:1], v23, s76, v[22:23]
	s_or_b32 s0, s23, s77
	v_add_u32_e32 v193, 16, v192
	s_add_u32 s0, s0, 0x18240000
	s_addc_u32 s1, s19, 0
	v_lshl_add_u64 v[194:195], s[0:1], 0, v[28:29]
	v_lshl_add_u64 v[196:197], s[0:1], 0, v[30:31]
	s_add_u32 s0, s55, 0x12a04000
	s_addc_u32 s1, s29, 0
	v_lshl_add_u64 v[198:199], s[0:1], 0, v[28:29]
	s_or_b32 s0, s23, s28
	v_lshlrev_b32_e32 v0, 3, v0
	v_cmp_lt_i32_e32 vcc, v208, v209
	s_add_u32 s0, s0, 0x16040000
	s_addc_u32 s1, s19, 0
	v_lshl_add_u64 v[200:201], s[0:1], 0, v[24:25]
	v_lshl_add_u64 v[202:203], s[0:1], 0, v[26:27]
	s_mov_b32 s12, 1
	v_mov_b32_e32 v215, 0
	v_mov_b32_e32 v214, 0xf149f2ca
	s_waitcnt vmcnt(21)
	ds_write_b128 v191, v[2:5]
	v_mul_lo_u32 v2, v23, s92
	v_add3_u32 v2, v184, v2, 16
	s_waitcnt vmcnt(20)
	ds_write_b128 v193, v[6:9]
	s_waitcnt vmcnt(19)
	ds_write_b128 v2, v[10:13] offset:256
	v_add_u32_e32 v2, 16, v184
	v_add_u32_e32 v2, 0x6400, v2
	s_waitcnt vmcnt(18)
	ds_write2_b64 v2, v[14:15], v[16:17] offset1:1
	v_add_u32_e32 v2, 16, v186
	v_add_u32_e32 v2, 0x6400, v2
	s_waitcnt vmcnt(17)
	ds_write2_b64 v2, v[18:19], v[20:21] offset1:1
	v_mad_u32_u24 v2, v37, s76, 16
	v_mul_i32_i24_e32 v3, 0xfffffef8, v37
	v_add_u32_e32 v187, v2, v32
	v_add3_u32 v213, v2, v3, v0
	v_cndmask_b32_e32 v2, v205, v208, vcc
	v_mov_b32_e32 v16, v1
	v_mov_b32_e32 v17, v1
	v_lshlrev_b32_e32 v185, 2, v2
	v_mov_b32_e32 v2, v1
	v_mov_b32_e32 v3, v1
	v_mov_b32_e32 v4, v1
	v_mov_b32_e32 v5, v1
	v_mov_b32_e32 v6, v1
	v_mov_b32_e32 v7, v1
	v_mov_b32_e32 v8, v1
	v_mov_b32_e32 v9, v1
	v_mov_b32_e32 v10, v1
	v_mov_b32_e32 v11, v1
	v_mov_b32_e32 v12, v1
	v_mov_b32_e32 v13, v1
	v_mov_b32_e32 v14, v1
	v_mov_b32_e32 v15, v1
	v_mov_b64_e32 v[32:33], v[16:17]
	v_mov_b64_e32 v[48:49], v[16:17]
	v_mov_b64_e32 v[64:65], v[16:17]
	v_mov_b64_e32 v[30:31], v[14:15]
	v_mov_b64_e32 v[28:29], v[12:13]
	v_mov_b64_e32 v[26:27], v[10:11]
	v_mov_b64_e32 v[24:25], v[8:9]
	v_mov_b64_e32 v[22:23], v[6:7]
	v_mov_b64_e32 v[20:21], v[4:5]
	v_mov_b64_e32 v[18:19], v[2:3]
	v_mov_b64_e32 v[46:47], v[14:15]
	v_mov_b64_e32 v[44:45], v[12:13]
	v_mov_b64_e32 v[42:43], v[10:11]
	v_mov_b64_e32 v[40:41], v[8:9]
	v_mov_b64_e32 v[38:39], v[6:7]
	v_mov_b64_e32 v[36:37], v[4:5]
	v_mov_b64_e32 v[34:35], v[2:3]
	v_mov_b64_e32 v[62:63], v[14:15]
	v_mov_b64_e32 v[60:61], v[12:13]
	v_mov_b64_e32 v[58:59], v[10:11]
	v_mov_b64_e32 v[56:57], v[8:9]
	v_mov_b64_e32 v[54:55], v[6:7]
	v_mov_b64_e32 v[52:53], v[4:5]
	v_mov_b64_e32 v[50:51], v[2:3]
	s_waitcnt vmcnt(5)
	s_waitcnt lgkmcnt(0)
	s_barrier
; template <int DQK, bool SWA>
; DI void attn_item(const P& p, char* shm, int b, int head, int qtile) {
;     ...
;         {
;             constexpr int NG = DQK / 32;
;             const char* kl = Kb + l31 * KST + 16 * hh;
;             bf16x8 ka[3][4];
; #pragma unroll
;             for (int g0 = 0; g0 < 2; ++g0)
; #pragma unroll
;                 for (int i = 0; i < 4; ++i) ka[g0][i] = *(const bf16x8*)(kl + (i & 1) * 32 * KST + 32 * (2 * g0 + (i >> 1)));
;             __builtin_amdgcn_s_setprio(1);
; #pragma unroll
;             for (int g = 0; g < NG; ++g) {
;                 if (g + 2 < NG) {
; #pragma unroll
;                     for (int i = 0; i < 4; ++i) ka[(g + 2) % 3][i] = *(const bf16x8*)(kl + (i & 1) * 32 * KST + 32 * (2 * (g + 2) + (i >> 1)));
;                 }
;                 __builtin_amdgcn_sched_barrier(0);
; #pragma unroll
;                 for (int i = 0; i < 4; ++i) sT[i & 1] = MFMA32(ka[g % 3][i], qf[2 * g + (i >> 1)], sT[i & 1]);
;                 __builtin_amdgcn_sched_barrier(0);
;             }
;             __builtin_amdgcn_s_setprio(0);
;         }
;         const char* vl = Vb + l31 * VST + 8 * hh;
;         bf16x8 va[2][4];
;         auto vfrag = [&](int g, int v) {
;             const char* vp = vl + v * 32 * VST + 32 * g;
;             const s16x4 vlo = *(const s16x4*)vp, vhi = *(const s16x4*)(vp + 16);
;             return (bf16x8)__builtin_shufflevector(vlo, vhi, 0, 1, 2, 3, 4, 5, 6, 7);
;         };
; #pragma unroll
;         for (int v = 0; v < 4; ++v) va[0][v] = vfrag(0, v);
;         __builtin_amdgcn_sched_barrier(0);
;         const bool band = SWA && t >= 4;
;         const int kl0 = 64 * (lo + t - 4), qs = myp - CTXL;
;         float mx = -3.0e38f;
; #pragma unroll
;         for (int kb = 0; kb < 2; ++kb)
; #pragma unroll
;             for (int r = 0; r < 16; ++r) {
;                 if (band) { const int dd = qs - (kl0 + kb * 32 + crow(r, hh)); if (dd > 128 || dd < -128) sT[kb][r] = -3.0e37f; }
;                 mx = fmaxf(mx, sT[kb][r]);
;             }
;         mx = fmaxf(mx, __shfl_xor(mx, 32));
;         const float cand = fmaxf(mrun, mx * sl2);
;         const bool grew = __any(cand - mrun > 8.f);
;         const float mn = grew ? cand : mrun;
;         const float alpha = __builtin_amdgcn_exp2f(mrun - mn);
;         mrun = mn;
;         float ls = 0.f;
; #pragma unroll
;         for (int kb = 0; kb < 2; ++kb)
.LBB0_1167:
	s_and_b32 s16, 1, s12
	s_cselect_b32 s0, 0, 0xa800
	v_add_u32_e32 v189, s0, v187
	ds_read_b128 v[66:69], v189
	ds_read_b128 v[166:169], v189 offset:32
	ds_read_b128 v[70:73], v189 offset:12800
	ds_read_b128 v[170:173], v189 offset:12832
	ds_read_b128 v[174:177], v189 offset:64
	ds_read_b128 v[178:181], v189 offset:96
	ds_read_b128 v[216:219], v189 offset:12864
	ds_read_b128 v[220:223], v189 offset:12896
	v_mov_b32_e32 v248, v214
	s_setprio 1
	ds_read_b128 v[224:227], v189 offset:128
	ds_read_b128 v[228:231], v189 offset:160
	ds_read_b128 v[232:235], v189 offset:12928
	ds_read_b128 v[236:239], v189 offset:12960
	s_waitcnt lgkmcnt(8)
	v_mfma_f32_32x32x16_bf16 v[82:97], v[66:69], v[142:145], 0
	v_mfma_f32_32x32x16_bf16 v[66:81], v[70:73], v[142:145], 0
	v_mfma_f32_32x32x16_bf16 v[82:97], v[166:169], v[138:141], v[82:97]
	v_mfma_f32_32x32x16_bf16 v[66:81], v[170:173], v[138:141], v[66:81]
	ds_read_b128 v[166:169], v189 offset:192
	ds_read_b128 v[170:173], v189 offset:224
	ds_read_b128 v[240:243], v189 offset:12992
	ds_read_b128 v[244:247], v189 offset:13024
	s_waitcnt lgkmcnt(8)
	v_mfma_f32_32x32x16_bf16 v[82:97], v[174:177], v[134:137], v[82:97]
	v_mfma_f32_32x32x16_bf16 v[66:81], v[216:219], v[134:137], v[66:81]
	v_mfma_f32_32x32x16_bf16 v[82:97], v[178:181], v[130:133], v[82:97]
	v_mfma_f32_32x32x16_bf16 v[66:81], v[220:223], v[130:133], v[66:81]
	ds_read_b128 v[174:177], v189 offset:256
	ds_read_b128 v[178:181], v189 offset:288
	ds_read_b128 v[216:219], v189 offset:13056
	ds_read_b128 v[220:223], v189 offset:13088
	s_waitcnt lgkmcnt(8)
	v_mfma_f32_32x32x16_bf16 v[82:97], v[224:227], v[126:129], v[82:97]
	v_mfma_f32_32x32x16_bf16 v[66:81], v[232:235], v[126:129], v[66:81]
	v_mfma_f32_32x32x16_bf16 v[82:97], v[228:231], v[122:125], v[82:97]
	v_mfma_f32_32x32x16_bf16 v[66:81], v[236:239], v[122:125], v[66:81]
	ds_read_b128 v[224:227], v189 offset:320
	ds_read_b128 v[228:231], v189 offset:352
	ds_read_b128 v[232:235], v189 offset:13120
	ds_read_b128 v[236:239], v189 offset:13152
	s_waitcnt lgkmcnt(8)
	v_mfma_f32_32x32x16_bf16 v[82:97], v[166:169], v[118:121], v[82:97]
	v_mfma_f32_32x32x16_bf16 v[66:81], v[240:243], v[118:121], v[66:81]
	v_mfma_f32_32x32x16_bf16 v[82:97], v[170:173], v[114:117], v[82:97]
	v_mfma_f32_32x32x16_bf16 v[66:81], v[244:247], v[114:117], v[66:81]
	s_waitcnt lgkmcnt(4)
	v_mfma_f32_32x32x16_bf16 v[82:97], v[174:177], v[110:113], v[82:97]
	v_mfma_f32_32x32x16_bf16 v[66:81], v[216:219], v[110:113], v[66:81]
	v_mfma_f32_32x32x16_bf16 v[82:97], v[178:181], v[106:109], v[82:97]
	v_mfma_f32_32x32x16_bf16 v[66:81], v[220:223], v[106:109], v[66:81]
	s_waitcnt lgkmcnt(0)
	v_mfma_f32_32x32x16_bf16 v[82:97], v[224:227], v[102:105], v[82:97]
	v_mfma_f32_32x32x16_bf16 v[66:81], v[232:235], v[102:105], v[66:81]
	v_mfma_f32_32x32x16_bf16 v[82:97], v[228:231], v[98:101], v[82:97]
	v_mfma_f32_32x32x16_bf16 v[66:81], v[236:239], v[98:101], v[66:81]
	s_setprio 0
	v_add_u32_e32 v178, s0, v213
	v_add_u32_e32 v219, 0x6000, v178
	v_add_u32_e32 v218, 0x7000, v178
	v_add_u32_e32 v217, 0x8000, v178
	v_add_u32_e32 v216, 0x9000, v178
	ds_read2_b64 v[166:169], v219 offset0:128 offset1:130
	ds_read2_b64 v[170:173], v218 offset0:160 offset1:162
	ds_read2_b64 v[174:177], v217 offset0:192 offset1:194
	ds_read2_b64 v[178:181], v216 offset0:224 offset1:226
	v_max3_f32 v189, v82, s61, v83
	v_max3_f32 v189, v189, v84, v85
	v_max3_f32 v189, v189, v86, v87
	v_max3_f32 v189, v189, v88, v89
	v_max3_f32 v189, v189, v90, v91
	v_max3_f32 v189, v189, v92, v93
	v_max3_f32 v189, v189, v94, v95
	v_max3_f32 v189, v189, v96, v97
	v_max3_f32 v189, v189, v66, v67
	v_max3_f32 v189, v189, v68, v69
	v_max3_f32 v189, v189, v70, v71
	v_max3_f32 v189, v189, v72, v73
	v_max3_f32 v189, v189, v74, v75
	v_max3_f32 v189, v189, v76, v77
	v_max3_f32 v189, v189, v78, v79
	v_max3_f32 v189, v189, v80, v81
	ds_bpermute_b32 v214, v185, v189
	v_max_f32_e32 v220, v248, v248
	s_waitcnt lgkmcnt(0)
	v_max_f32_e32 v214, v214, v214
	v_max_f32_e32 v189, v189, v214
	v_mul_f32_e32 v189, 0x3dd53b94, v189
	v_max_f32_e32 v189, v220, v189
	v_sub_f32_e32 v214, v189, v248
	v_cmp_lt_f32_e32 vcc, s63, v214
	s_cmp_eq_u64 vcc, 0
	s_cselect_b64 s[0:1], -1, 0
	v_cndmask_b32_e64 v214, v189, v248, s[0:1]
	v_fma_f32 v82, v82, s80, -v214
	v_fma_f32 v83, v83, s80, -v214
	v_exp_f32_e32 v82, v82
	v_exp_f32_e32 v83, v83
	v_fma_f32 v84, v84, s80, -v214
	v_exp_f32_e32 v84, v84
	v_fma_f32 v85, v85, s80, -v214
	v_exp_f32_e32 v85, v85
	v_fma_f32 v86, v86, s80, -v214
	v_add_f32_e32 v189, 0, v82
	v_exp_f32_e32 v86, v86
	v_fma_f32 v87, v87, s80, -v214
	v_add_f32_e32 v189, v83, v189
	v_exp_f32_e32 v87, v87
	v_fma_f32 v88, v88, s80, -v214
	v_add_f32_e32 v189, v84, v189
	v_exp_f32_e32 v88, v88
	v_fma_f32 v89, v89, s80, -v214
	v_add_f32_e32 v189, v85, v189
	v_exp_f32_e32 v89, v89
	v_fma_f32 v90, v90, s80, -v214
	v_add_f32_e32 v189, v86, v189
	v_exp_f32_e32 v90, v90
	v_fma_f32 v91, v91, s80, -v214
	v_add_f32_e32 v189, v87, v189
	v_exp_f32_e32 v91, v91
	v_fma_f32 v92, v92, s80, -v214
	v_add_f32_e32 v189, v88, v189
	v_exp_f32_e32 v92, v92
	v_fma_f32 v93, v93, s80, -v214
	v_add_f32_e32 v189, v89, v189
	v_exp_f32_e32 v93, v93
	v_fma_f32 v94, v94, s80, -v214
	v_add_f32_e32 v189, v90, v189
	v_exp_f32_e32 v94, v94
	v_fma_f32 v95, v95, s80, -v214
	v_add_f32_e32 v189, v91, v189
	v_exp_f32_e32 v95, v95
	v_fma_f32 v96, v96, s80, -v214
	v_add_f32_e32 v189, v92, v189
	v_exp_f32_e32 v96, v96
	v_fma_f32 v97, v97, s80, -v214
	v_add_f32_e32 v189, v93, v189
	v_exp_f32_e32 v97, v97
	v_fma_f32 v66, v66, s80, -v214
	v_add_f32_e32 v189, v94, v189
	v_exp_f32_e32 v220, v66
	v_fma_f32 v66, v67, s80, -v214
	v_add_f32_e32 v189, v95, v189
; template <int DQK, bool SWA>
; DI void attn_item(const P& p, char* shm, int b, int head, int qtile) {
;     ...
;         float ls = 0.f;
; #pragma unroll
;         for (int kb = 0; kb < 2; ++kb)
; #pragma unroll
;             for (int r = 0; r < 16; ++r) { const float pv = __builtin_amdgcn_exp2f(fmaf(sT[kb][r], sl2, -mn)); sT[kb][r] = pv; ls += pv; }
;         ls += __shfl_xor(ls, 32);
;         lrun = lrun * alpha + ls;
;         if (grew) {
; #pragma unroll
;             for (int v = 0; v < 4; ++v) oT[v] *= alpha;
;         }
	v_exp_f32_e32 v67, v66
	v_fma_f32 v66, v68, s80, -v214
	v_add_f32_e32 v189, v96, v189
	v_exp_f32_e32 v68, v66
	v_fma_f32 v66, v69, s80, -v214
	v_add_f32_e32 v189, v97, v189
	v_exp_f32_e32 v69, v66
	v_fma_f32 v70, v70, s80, -v214
	v_add_f32_e32 v66, v220, v189
	v_exp_f32_e32 v70, v70
	v_fma_f32 v71, v71, s80, -v214
	v_add_f32_e32 v66, v67, v66
	v_exp_f32_e32 v71, v71
	v_fma_f32 v72, v72, s80, -v214
	v_add_f32_e32 v66, v68, v66
	v_exp_f32_e32 v72, v72
	v_fma_f32 v73, v73, s80, -v214
	v_add_f32_e32 v66, v69, v66
	v_exp_f32_e32 v73, v73
	v_fma_f32 v74, v74, s80, -v214
	v_add_f32_e32 v66, v70, v66
	v_exp_f32_e32 v74, v74
	v_fma_f32 v75, v75, s80, -v214
	v_add_f32_e32 v66, v71, v66
	v_exp_f32_e32 v75, v75
	v_fma_f32 v76, v76, s80, -v214
	v_add_f32_e32 v66, v72, v66
	v_exp_f32_e32 v76, v76
	v_fma_f32 v77, v77, s80, -v214
	v_add_f32_e32 v66, v73, v66
	v_exp_f32_e32 v77, v77
	v_fma_f32 v78, v78, s80, -v214
	v_add_f32_e32 v66, v74, v66
	v_exp_f32_e32 v78, v78
	v_fma_f32 v79, v79, s80, -v214
	v_add_f32_e32 v66, v75, v66
	v_exp_f32_e32 v79, v79
	v_fma_f32 v80, v80, s80, -v214
	v_add_f32_e32 v66, v76, v66
	v_exp_f32_e32 v80, v80
	v_fma_f32 v81, v81, s80, -v214
	v_add_f32_e32 v66, v77, v66
	v_exp_f32_e32 v81, v81
	v_add_f32_e32 v66, v78, v66
	v_add_f32_e32 v66, v79, v66
	v_add_f32_e32 v66, v80, v66
	v_add_f32_e32 v189, v81, v66
	v_sub_f32_e32 v222, v248, v214
	ds_bpermute_b32 v221, v185, v189
	v_exp_f32_e32 v66, v222
	s_cbranch_vccz .LBB0_1169
	v_pk_mul_f32 v[64:65], v[64:65], v[66:67] op_sel_hi:[1,0]
	v_pk_mul_f32 v[62:63], v[62:63], v[66:67] op_sel_hi:[1,0]
	v_pk_mul_f32 v[60:61], v[60:61], v[66:67] op_sel_hi:[1,0]
	v_pk_mul_f32 v[58:59], v[58:59], v[66:67] op_sel_hi:[1,0]
	v_pk_mul_f32 v[56:57], v[56:57], v[66:67] op_sel_hi:[1,0]
	v_pk_mul_f32 v[54:55], v[54:55], v[66:67] op_sel_hi:[1,0]
	v_pk_mul_f32 v[52:53], v[52:53], v[66:67] op_sel_hi:[1,0]
	v_pk_mul_f32 v[50:51], v[50:51], v[66:67] op_sel_hi:[1,0]
	v_pk_mul_f32 v[48:49], v[48:49], v[66:67] op_sel_hi:[1,0]
	v_pk_mul_f32 v[46:47], v[46:47], v[66:67] op_sel_hi:[1,0]
	v_pk_mul_f32 v[44:45], v[44:45], v[66:67] op_sel_hi:[1,0]
	v_pk_mul_f32 v[42:43], v[42:43], v[66:67] op_sel_hi:[1,0]
	v_pk_mul_f32 v[40:41], v[40:41], v[66:67] op_sel_hi:[1,0]
	v_pk_mul_f32 v[38:39], v[38:39], v[66:67] op_sel_hi:[1,0]
	v_pk_mul_f32 v[36:37], v[36:37], v[66:67] op_sel_hi:[1,0]
	v_pk_mul_f32 v[34:35], v[34:35], v[66:67] op_sel_hi:[1,0]
	v_pk_mul_f32 v[32:33], v[32:33], v[66:67] op_sel_hi:[1,0]
	v_pk_mul_f32 v[30:31], v[30:31], v[66:67] op_sel_hi:[1,0]
	v_pk_mul_f32 v[28:29], v[28:29], v[66:67] op_sel_hi:[1,0]
	v_pk_mul_f32 v[26:27], v[26:27], v[66:67] op_sel_hi:[1,0]
	v_pk_mul_f32 v[24:25], v[24:25], v[66:67] op_sel_hi:[1,0]
	v_pk_mul_f32 v[22:23], v[22:23], v[66:67] op_sel_hi:[1,0]
	v_pk_mul_f32 v[20:21], v[20:21], v[66:67] op_sel_hi:[1,0]
	v_pk_mul_f32 v[18:19], v[18:19], v[66:67] op_sel_hi:[1,0]
	v_pk_mul_f32 v[16:17], v[16:17], v[66:67] op_sel_hi:[1,0]
	v_pk_mul_f32 v[14:15], v[14:15], v[66:67] op_sel_hi:[1,0]
	v_pk_mul_f32 v[12:13], v[12:13], v[66:67] op_sel_hi:[1,0]
	v_pk_mul_f32 v[10:11], v[10:11], v[66:67] op_sel_hi:[1,0]
	v_pk_mul_f32 v[8:9], v[8:9], v[66:67] op_sel_hi:[1,0]
	v_pk_mul_f32 v[6:7], v[6:7], v[66:67] op_sel_hi:[1,0]
	v_pk_mul_f32 v[4:5], v[4:5], v[66:67] op_sel_hi:[1,0]
	v_pk_mul_f32 v[2:3], v[2:3], v[66:67] op_sel_hi:[1,0]
; #define MFMA32(a, b, c) __builtin_amdgcn_mfma_f32_32x32x16_bf16((a), (b), (c), 0, 0, 0)
; template <int DQK, bool SWA>
; DI void attn_item(const P& p, char* shm, int b, int head, int qtile) {
;     ...
;     auto store_tile = [&](int t) {
;         const int bo = (t & 1) * (64 * KST + 128 * VST);
;         *(bf16x8*)(Ks + bo + klds0) = kreg[0];
;         *(bf16x8*)(Ks + bo + klds1) = kreg[1];
;         if (!SWA) *(bf16x8*)(Ks + bo + klds2) = kreg[NKL - 1];
; #pragma unroll
;         for (int i = 0; i < 2; ++i) {
;             const s16x4 w0 = __builtin_shufflevector(vreg[i], vreg[i], 0, 1, 2, 3), w1 = __builtin_shufflevector(vreg[i], vreg[i], 4, 5, 6, 7);
;             char* dstv = Vs + bo + (i ? vlds1 : vlds0);
;             *(s16x4*)dstv = w0;
;             *(s16x4*)(dstv + 8) = w1;
;         }
;     ...
;         bf16x8 pf[2][2];
; #pragma unroll
;         for (int kb = 0; kb < 2; ++kb)
; #pragma unroll
;             for (int s2 = 0; s2 < 2; ++s2)
;                 pf[kb][s2] = pack8(sT[kb][8 * s2], sT[kb][8 * s2 + 1], sT[kb][8 * s2 + 2], sT[kb][8 * s2 + 3], sT[kb][8 * s2 + 4], sT[kb][8 * s2 + 5], sT[kb][8 * s2 + 6], sT[kb][8 * s2 + 7]);
;         if (t + 1 < ntiles) store_tile(t + 1);
;         if (t + 2 < ntiles) load_tile(t + 2);
;         {
;             __builtin_amdgcn_s_setprio(1);
; #pragma unroll
;             for (int g = 0; g < 4; ++g) {
;                 if (g + 1 < 4) {
; #pragma unroll
;                     for (int v = 0; v < 4; ++v) va[(g + 1) & 1][v] = vfrag(g + 1, v);
;                 }
;                 __builtin_amdgcn_sched_barrier(0);
; #pragma unroll
;                 for (int v = 0; v < 4; ++v) oT[v] = MFMA32(va[g & 1][v], pf[g >> 1][g & 1], oT[v]);
;                 __builtin_amdgcn_sched_barrier(0);
;             }
;             __builtin_amdgcn_s_setprio(0);
;         }
;         __syncthreads();
.LBB0_1169:
	s_cmp_eq_u32 s16, 1
	s_cselect_b32 s0, 0xa800, 0
	s_add_i32 s0, s0, 16
	v_add_u32_e32 v222, s0, v190
	s_waitcnt vmcnt(4)
	ds_write_b128 v222, v[146:149]
	v_add_u32_e32 v146, s0, v192
	s_waitcnt vmcnt(3)
	ds_write_b128 v146, v[150:153]
	v_add_u32_e32 v146, s0, v188
	s_waitcnt vmcnt(2)
	ds_write_b128 v146, v[154:157] offset:256
	v_add_u32_e32 v146, s0, v184
	v_add_u32_e32 v146, 0x6400, v146
	s_waitcnt vmcnt(1)
	ds_write2_b64 v146, v[162:163], v[164:165] offset1:1
	v_add_u32_e32 v146, s0, v186
	v_add_u32_e32 v146, 0x6400, v146
	s_waitcnt vmcnt(0)
	ds_write2_b64 v146, v[158:159], v[160:161] offset1:1
	v_lshl_add_u64 v[146:147], s[26:27], 0, v[200:201]
	v_lshl_add_u64 v[150:151], s[26:27], 0, v[202:203]
	v_lshl_add_u64 v[154:155], s[26:27], 0, v[198:199]
	v_lshl_add_u64 v[158:159], s[26:27], 0, v[194:195]
	global_load_dwordx4 v[146:149], v[146:147], off
	s_nop 0
	global_load_dwordx4 v[150:153], v[150:151], off
	s_nop 0
	global_load_dwordx4 v[154:157], v[154:155], off
	s_nop 0
	global_load_dwordx4 v[162:165], v[158:159], off
	v_lshl_add_u64 v[158:159], s[26:27], 0, v[196:197]
	global_load_dwordx4 v[158:161], v[158:159], off
	s_waitcnt lgkmcnt(5)
	v_add_f32_e32 v189, v189, v221
	v_fmac_f32_e32 v189, v215, v66
	v_cvt_pk_bf16_f32 v82, v82, v83
	v_cvt_pk_bf16_f32 v83, v84, v85
	v_cvt_pk_bf16_f32 v84, v86, v87
	v_cvt_pk_bf16_f32 v85, v88, v89
	v_cvt_pk_bf16_f32 v86, v90, v91
	v_cvt_pk_bf16_f32 v87, v92, v93
	v_cvt_pk_bf16_f32 v88, v94, v95
	v_cvt_pk_bf16_f32 v89, v96, v97
	v_cvt_pk_bf16_f32 v66, v220, v67
	v_cvt_pk_bf16_f32 v67, v68, v69
	v_cvt_pk_bf16_f32 v68, v70, v71
	v_cvt_pk_bf16_f32 v69, v72, v73
	v_cvt_pk_bf16_f32 v70, v74, v75
	v_cvt_pk_bf16_f32 v71, v76, v77
	v_cvt_pk_bf16_f32 v72, v78, v79
	v_cvt_pk_bf16_f32 v73, v80, v81
	s_setprio 1
	ds_read2_b64 v[74:77], v219 offset0:132 offset1:134
	ds_read2_b64 v[78:81], v218 offset0:164 offset1:166
	ds_read2_b64 v[90:93], v217 offset0:196 offset1:198
	ds_read2_b64 v[94:97], v216 offset0:228 offset1:230
	v_mfma_f32_32x32x16_bf16 v[50:65], v[166:169], v[82:85], v[50:65]
	v_mfma_f32_32x32x16_bf16 v[34:49], v[170:173], v[82:85], v[34:49]
	v_mfma_f32_32x32x16_bf16 v[18:33], v[174:177], v[82:85], v[18:33]
	v_mfma_f32_32x32x16_bf16 v[2:17], v[178:181], v[82:85], v[2:17]
	ds_read2_b64 v[82:85], v219 offset0:136 offset1:138
	ds_read2_b64 v[166:169], v218 offset0:168 offset1:170
	ds_read2_b64 v[170:173], v217 offset0:200 offset1:202
	ds_read2_b64 v[174:177], v216 offset0:232 offset1:234
	s_waitcnt lgkmcnt(4)
	v_mfma_f32_32x32x16_bf16 v[50:65], v[74:77], v[86:89], v[50:65]
	v_mfma_f32_32x32x16_bf16 v[34:49], v[78:81], v[86:89], v[34:49]
	v_mfma_f32_32x32x16_bf16 v[18:33], v[90:93], v[86:89], v[18:33]
	v_mfma_f32_32x32x16_bf16 v[2:17], v[94:97], v[86:89], v[2:17]
	ds_read2_b64 v[74:77], v219 offset0:140 offset1:142
	ds_read2_b64 v[78:81], v218 offset0:172 offset1:174
	ds_read2_b64 v[86:89], v217 offset0:204 offset1:206
	ds_read2_b64 v[90:93], v216 offset0:236 offset1:238
	s_waitcnt lgkmcnt(4)
	v_mfma_f32_32x32x16_bf16 v[50:65], v[82:85], v[66:69], v[50:65]
	v_mfma_f32_32x32x16_bf16 v[34:49], v[166:169], v[66:69], v[34:49]
	v_mfma_f32_32x32x16_bf16 v[18:33], v[170:173], v[66:69], v[18:33]
	v_mfma_f32_32x32x16_bf16 v[2:17], v[174:177], v[66:69], v[2:17]
	s_waitcnt lgkmcnt(0)
	v_mfma_f32_32x32x16_bf16 v[50:65], v[74:77], v[70:73], v[50:65]
	v_mfma_f32_32x32x16_bf16 v[34:49], v[78:81], v[70:73], v[34:49]
	v_mfma_f32_32x32x16_bf16 v[18:33], v[86:89], v[70:73], v[18:33]
	v_mfma_f32_32x32x16_bf16 v[2:17], v[90:93], v[70:73], v[2:17]
	s_setprio 0
	s_add_i32 s12, s12, 1
	s_mov_b64 s[0:1], 0x2000
	v_lshl_add_u64 v[194:195], v[194:195], 0, s[14:15]
	v_lshl_add_u64 v[196:197], v[196:197], 0, s[14:15]
	v_lshl_add_u64 v[198:199], v[198:199], 0, s[0:1]
	v_lshl_add_u64 v[200:201], v[200:201], 0, s[14:15]
	s_cmpk_eq_i32 s12, 0x43
	v_lshl_add_u64 v[202:203], v[202:203], 0, s[14:15]
	s_barrier
	s_cbranch_scc1 .LBB0_1171
	v_mov_b32_e32 v215, v189
	s_branch .LBB0_1167
